# scan static units: compute waves at s_setprio 2 (helper waves only fill bubbles)
# baseline (speedup 1.0000x reference)
.LBB0_489:
	s_andn2_saveexec_b64 s[20:21], s[20:21]
	s_cbranch_execz .LBB0_495
	s_setprio 2
	s_waitcnt vmcnt(14)
	v_mov_b32_e32 v66, 0
	s_mov_b32 s26, 0
	s_mov_b64 s[22:23], 0
	s_waitcnt vmcnt(13)
	v_mov_b32_e32 v67, v66
	v_mov_b32_e32 v64, v66
	v_mov_b32_e32 v65, v66
	v_mov_b32_e32 v26, v66
	v_mov_b32_e32 v27, v66
	v_mov_b32_e32 v24, v66
	v_mov_b32_e32 v25, v66
	s_barrier

.LBB0_492:
	ds_read_b128 v[104:107], v30
	ds_read_b128 v[108:111], v30 offset:16
	ds_read_b128 v[112:115], v30 offset:512
	ds_read_b128 v[116:119], v30 offset:528
	s_waitcnt lgkmcnt(7)
	v_pk_add_f32 v[120:121], v[20:21], v[66:67] op_sel_hi:[0,1] neg_lo:[0,1] neg_hi:[0,1]
	s_waitcnt lgkmcnt(5)
	v_pk_fma_f32 v[66:67], v[12:13], v[120:121], v[66:67]
	v_pk_add_f32 v[12:13], v[20:21], v[64:65] op_sel_hi:[0,1] neg_lo:[0,1] neg_hi:[0,1]
	v_pk_fma_f32 v[64:65], v[14:15], v[12:13], v[64:65]
	v_pk_add_f32 v[12:13], v[20:21], v[26:27] op_sel_hi:[0,1] neg_lo:[0,1] neg_hi:[0,1]
	v_pk_mul_f32 v[0:1], v[0:1], v[66:67]
	s_add_i32 s36, s36, 4
	v_pk_fma_f32 v[26:27], v[8:9], v[12:13], v[26:27]
	v_pk_add_f32 v[8:9], v[20:21], v[24:25] op_sel_hi:[0,1] neg_lo:[0,1] neg_hi:[0,1]
	v_pk_fma_f32 v[0:1], v[64:65], v[2:3], v[0:1]
	v_pk_add_f32 v[120:121], v[20:21], v[66:67] op_sel:[1,0] neg_lo:[0,1] neg_hi:[0,1]
	s_and_b32 s37, s36, 28
	v_pk_fma_f32 v[24:25], v[10:11], v[8:9], v[24:25]
	s_waitcnt lgkmcnt(4)
	v_pk_fma_f32 v[0:1], v[26:27], v[4:5], v[0:1]
	s_waitcnt lgkmcnt(1)
	v_pk_fma_f32 v[66:67], v[112:113], v[120:121], v[66:67]
	v_pk_add_f32 v[112:113], v[20:21], v[64:65] op_sel:[1,0] neg_lo:[0,1] neg_hi:[0,1]
	v_lshl_add_u32 v16, s37, 2, v53
	v_pk_fma_f32 v[0:1], v[24:25], v[6:7], v[0:1]
	v_pk_fma_f32 v[64:65], v[114:115], v[112:113], v[64:65]
	v_pk_add_f32 v[112:113], v[20:21], v[26:27] op_sel:[1,0] neg_lo:[0,1] neg_hi:[0,1]
	v_pk_add_f32 v[20:21], v[20:21], v[24:25] op_sel:[1,0] neg_lo:[0,1] neg_hi:[0,1]
	ds_read_b128 v[16:19], v16
	v_add_f32_e32 v55, v0, v1
	ds_read_b128 v[0:3], v30 offset:1024
	ds_read_b128 v[4:7], v30 offset:1040
	ds_read_b128 v[8:11], v30 offset:1536
	ds_read_b128 v[12:15], v30 offset:1552
	s_waitcnt lgkmcnt(5)
	v_pk_fma_f32 v[20:21], v[118:119], v[20:21], v[24:25]
	v_pk_mul_f32 v[24:25], v[104:105], v[66:67]
	v_pk_fma_f32 v[116:117], v[116:117], v[112:113], v[26:27]
	v_pk_fma_f32 v[24:25], v[64:65], v[106:107], v[24:25]
	v_pk_add_f32 v[118:119], v[22:23], v[66:67] op_sel_hi:[0,1] neg_lo:[0,1] neg_hi:[0,1]
	v_pk_fma_f32 v[24:25], v[116:117], v[108:109], v[24:25]
	s_waitcnt lgkmcnt(1)
	v_pk_fma_f32 v[66:67], v[8:9], v[118:119], v[66:67]
	v_pk_fma_f32 v[24:25], v[20:21], v[110:111], v[24:25]
	v_pk_add_f32 v[8:9], v[22:23], v[64:65] op_sel_hi:[0,1] neg_lo:[0,1] neg_hi:[0,1]
	v_add_f32_e32 v57, v24, v25
	ds_read_b128 v[104:107], v30 offset:2048
	ds_read_b128 v[108:111], v30 offset:2064
	ds_read_b128 v[24:27], v30 offset:2560
	ds_read_b128 v[112:115], v30 offset:2576
	v_pk_fma_f32 v[64:65], v[10:11], v[8:9], v[64:65]
	v_pk_add_f32 v[8:9], v[22:23], v[116:117] op_sel_hi:[0,1] neg_lo:[0,1] neg_hi:[0,1]
	s_waitcnt lgkmcnt(4)
	v_pk_fma_f32 v[116:117], v[12:13], v[8:9], v[116:117]
	v_pk_add_f32 v[8:9], v[22:23], v[20:21] op_sel_hi:[0,1] neg_lo:[0,1] neg_hi:[0,1]
	v_mov_b32_e32 v22, v23
	v_pk_mul_f32 v[0:1], v[0:1], v[66:67]
	v_pk_add_f32 v[118:119], v[22:23], v[66:67] op_sel_hi:[0,1] neg_lo:[0,1] neg_hi:[0,1]
	v_pk_fma_f32 v[20:21], v[14:15], v[8:9], v[20:21]
	v_pk_fma_f32 v[0:1], v[64:65], v[2:3], v[0:1]
	s_waitcnt lgkmcnt(1)
	v_pk_fma_f32 v[66:67], v[24:25], v[118:119], v[66:67]
	v_pk_add_f32 v[24:25], v[22:23], v[64:65] op_sel_hi:[0,1] neg_lo:[0,1] neg_hi:[0,1]
	v_pk_fma_f32 v[0:1], v[116:117], v[4:5], v[0:1]
	v_pk_fma_f32 v[64:65], v[26:27], v[24:25], v[64:65]
	v_pk_add_f32 v[24:25], v[22:23], v[116:117] op_sel_hi:[0,1] neg_lo:[0,1] neg_hi:[0,1]
	v_pk_add_f32 v[22:23], v[22:23], v[20:21] op_sel_hi:[0,1] neg_lo:[0,1] neg_hi:[0,1]
	v_pk_fma_f32 v[0:1], v[20:21], v[6:7], v[0:1]
	s_waitcnt lgkmcnt(0)
	v_pk_fma_f32 v[26:27], v[112:113], v[24:25], v[116:117]
	v_pk_fma_f32 v[24:25], v[114:115], v[22:23], v[20:21]
	v_pk_mul_f32 v[20:21], v[104:105], v[66:67]
	v_add_f32_e32 v59, v0, v1
	v_pk_fma_f32 v[20:21], v[64:65], v[106:107], v[20:21]
	ds_read_b128 v[0:3], v30 offset:3072
	ds_read_b128 v[4:7], v30 offset:3088
	ds_read_b128 v[12:15], v30 offset:3584
	ds_read_b128 v[8:11], v30 offset:3600
	v_pk_fma_f32 v[20:21], v[26:27], v[108:109], v[20:21]
	v_cndmask_b32_e64 v22, v55, v57, s[12:13]
	v_pk_fma_f32 v[20:21], v[24:25], v[110:111], v[20:21]
	v_add_u32_e32 v30, 0x1000, v30
	v_add_f32_e32 v20, v20, v21
	v_cndmask_b32_e64 v21, v57, v55, s[12:13]
	v_cndmask_b32_e64 v23, v20, v59, s[12:13]
	v_cndmask_b32_e64 v20, v59, v20, s[12:13]
	v_add_f32_dpp v21, v22, v21 quad_perm:[1,0,3,2] row_mask:0xf bank_mask:0xf bound_ctrl:1
	s_cmp_lt_u32 s36, s27
	v_add_f32_dpp v20, v20, v23 quad_perm:[1,0,3,2] row_mask:0xf bank_mask:0xf bound_ctrl:1
	v_cndmask_b32_e64 v22, v20, v21, s[14:15]
	v_cndmask_b32_e64 v20, v21, v20, s[14:15]
	s_nop 1
	v_add_f32_dpp v20, v20, v22 quad_perm:[2,3,0,1] row_mask:0xf bank_mask:0xf bound_ctrl:1
	ds_write_b32 v49, v20
	v_mov_b64_e32 v[22:23], v[18:19]
	v_add_u32_e32 v49, 0x400, v49
	v_mov_b64_e32 v[20:21], v[16:17]
	s_cbranch_scc1 .LBB0_492
	s_add_i32 s26, s26, 1
	s_xor_b64 s[22:23], s[22:23], -1
	s_cmpk_eq_i32 s26, 0x201
	s_waitcnt lgkmcnt(0)
	s_barrier
	s_cbranch_scc0 .LBB0_491
	s_setprio 0
	s_lshl_b32 s22, s2, 16
	s_and_b32 s22, s22, 0xf0000
	s_mov_b32 s23, s31
	v_lshl_add_u64 v[0:1], v[34:35], 0, s[22:23]
	v_lshl_add_u64 v[0:1], s[30:31], 2, v[0:1]
	v_mov_b32_e32 v53, v31
	v_lshl_add_u64 v[0:1], v[0:1], 0, v[52:53]
	global_store_dword v[0:1], v66, off
	global_store_dword v[0:1], v67, off offset:512
	global_store_dword v[0:1], v64, off offset:1024
	global_store_dword v[0:1], v65, off offset:1536
	global_store_dword v[0:1], v26, off offset:2048
	global_store_dword v[0:1], v27, off offset:2560
	global_store_dword v[0:1], v24, off offset:3072
	global_store_dword v[0:1], v25, off offset:3584

.LBB0_586:
	s_andn2_saveexec_b64 s[20:21], s[48:49]
	s_cbranch_execz .LBB0_451
	s_setprio 2
	v_mov_b32_e32 v30, v31
	s_mov_b32 s26, 0
	s_mov_b64 s[22:23], 0
	s_waitcnt vmcnt(33)
	v_mov_b64_e32 v[16:17], v[30:31]
	s_waitcnt vmcnt(31)
	v_mov_b64_e32 v[18:19], v[30:31]
	s_barrier

.LrwT_drain:
	v_pk_mul_f32 v[4:5], v[216:217], v[16:17]
	v_pk_fma_f32 v[4:5], v[18:19], v[218:219], v[4:5]
	s_nop 0
	v_add_f32_e32 v27, v4, v5
	v_cndmask_b32_e64 v6, v25, v24, s[12:13]
	v_cndmask_b32_e64 v7, v24, v25, s[12:13]
	v_cndmask_b32_e64 v55, v27, v26, s[12:13]
	v_cndmask_b32_e64 v57, v26, v27, s[12:13]
	v_add_f32_dpp v6, v7, v6 quad_perm:[1,0,3,2] row_mask:0xf bank_mask:0xf bound_ctrl:1
	v_pk_mul_f32 v[16:17], v[16:17], v[108:109]
	v_add_f32_dpp v55, v57, v55 quad_perm:[1,0,3,2] row_mask:0xf bank_mask:0xf bound_ctrl:1
	v_cndmask_b32_e64 v57, v6, v55, s[14:15]
	v_cndmask_b32_e64 v7, v55, v6, s[14:15]
	v_pk_mul_f32 v[18:19], v[18:19], v[110:111]
	v_add_f32_dpp v7, v57, v7 quad_perm:[2,3,0,1] row_mask:0xf bank_mask:0xf bound_ctrl:1
	s_add_i32 s26, s26, 1
	s_cmpk_eq_i32 s26, 0x201
	v_add_f32_dpp v7, v7, v7 row_ror:4 row_mask:0xf bank_mask:0xf bound_ctrl:1
	s_nop 1
	v_add_f32_dpp v7, v7, v7 row_ror:8 row_mask:0xf bank_mask:0xf bound_ctrl:1
	ds_write_b32 v53, v7 offset:256
	s_waitcnt lgkmcnt(0)
	s_barrier
	s_cbranch_scc0 .LrwT_tile
	s_setprio 0
	s_lshl_b32 s22, s2, 14
	s_and_b32 s22, s22, 0x7c000
	s_add_u32 s22, s67, s22
	v_lshl_or_b32 v0, s47, 10, v70
	s_addc_u32 s23, s92, 0
	v_ashrrev_i32_e32 v1, 31, v0
	v_lshl_add_u64 v[0:1], v[0:1], 2, s[22:23]
	v_mov_b32_e32 v55, v31
	v_lshl_add_u64 v[0:1], v[0:1], 0, v[54:55]
	global_store_dwordx4 v[0:1], v[16:19], off
	s_branch .LBB0_451
